# gdn scan producer: O-tile write-back with both LDS reads up front and scalar-base + 32-bit-offset stores
# baseline (speedup 1.0000x reference)
; __device__ __forceinline__ void gdn_scan(const Ctx& c, const Params& p, int e) {
;     ...
;         if (producer) {
;             int pt_ = ptid; asm volatile("" : "+v"(pt_));
;             u32x4 tq[4], tk[4], tw[4], tu[4], tqk[2];
;             const int prow = pt_ >> 4, pc8 = (pt_ & 15) * 8;
;             const int qrow = pt_ >> 3, qc8 = (pt_ & 7) * 8;
;             GDN_LOAD_TILES(0); GDN_STORE_TILES();
.LBB0_530:
	s_and_b64 vcc, exec, s[2:3]
	s_cbranch_vccz .LBB0_521
	s_mul_hi_i32 s2, s20, 0x2aaaaaab
	s_lshr_b32 s3, s2, 31
	s_add_i32 s2, s2, s3
	s_mul_i32 s3, s2, 6
	s_sub_i32 s3, s20, s3
	s_waitcnt vmcnt(0)
	v_mov_b32_e32 v97, v165
	s_lshl_b32 s4, s2, 13
	v_ashrrev_i32_e32 v64, 4, v97
	v_lshlrev_b32_e32 v1, 3, v97
	s_lshl_b32 s2, s3, 7
	s_waitcnt lgkmcnt(0)
	v_and_b32_e32 v12, 0x78, v1
	s_ashr_i32 s5, s4, 31
	v_ashrrev_i32_e32 v65, 31, v64
	s_ashr_i32 s3, s2, 31
	v_lshl_add_u64 v[2:3], v[64:65], 0, s[4:5]
	v_or_b32_e32 v102, s2, v12
	v_mov_b32_e32 v103, s3
	s_movk_i32 s35, 0x300
	v_and_b32_e32 v66, 56, v1
	v_mad_u64_u32 v[6:7], s[20:21], v2, s35, v[102:103]
	v_add_u32_e32 v1, 0x100, v97
	v_mad_i32_i24 v7, v3, s35, v7
	v_mov_b64_e32 v[10:11], s[16:17]
	v_ashrrev_i32_e32 v106, 4, v1
	v_mad_u64_u32 v[4:5], s[20:21], v2, s69, v[10:11]
	v_lshlrev_b64 v[6:7], 1, v[6:7]
	v_ashrrev_i32_e32 v107, 31, v106
	v_mad_i32_i24 v5, v3, s69, v5
	s_lshl_b64 s[20:21], s[2:3], 1
	v_lshlrev_b32_e32 v114, 4, v97
	v_lshl_add_u64 v[68:69], s[8:9], 0, v[6:7]
	v_lshl_add_u64 v[78:79], s[6:7], 0, v[6:7]
	v_lshl_add_u64 v[6:7], v[106:107], 0, s[4:5]
	v_lshl_add_u64 v[8:9], v[4:5], 0, s[20:21]
	v_lshlrev_b32_e32 v104, 1, v12
	v_mov_b32_e32 v105, v0
	v_and_b32_e32 v4, 0x80, v114
	v_mov_b32_e32 v5, v0
	v_mad_u64_u32 v[32:33], s[2:3], v6, s69, v[10:11]
	v_lshl_add_u64 v[14:15], v[8:9], 0, v[104:105]
	v_lshl_add_u64 v[12:13], v[8:9], 0, v[4:5]
	v_lshlrev_b32_e32 v8, 1, v66
	v_mov_b32_e32 v9, v0
	v_mad_i32_i24 v33, v7, s69, v33
	v_lshl_add_u64 v[12:13], v[12:13], 0, v[8:9]
	v_lshl_add_u64 v[32:33], v[32:33], 0, s[20:21]
	global_load_dwordx4 v[16:19], v[14:15], off offset:1536
	global_load_dwordx4 v[20:23], v[12:13], off offset:3072
	v_add_co_u32_e32 v12, vcc, s47, v14
	v_lshl_add_u64 v[32:33], v[32:33], 0, v[4:5]
	s_nop 0
	v_addc_co_u32_e32 v13, vcc, 0, v15, vcc
	v_lshl_add_u64 v[36:37], v[32:33], 0, v[8:9]
	s_movk_i32 s0, 0x6000
	global_load_dwordx4 v[24:27], v[68:69], off
	global_load_dwordx4 v[28:31], v[78:79], off
	global_load_dwordx4 v[32:35], v[12:13], off offset:2048
	s_nop 0
	global_load_dwordx4 v[36:39], v[36:37], off offset:3072
	v_add_co_u32_e32 v12, vcc, s0, v68
	s_mov_b32 s39, 0x3c000
	s_nop 0
	v_addc_co_u32_e32 v13, vcc, 0, v69, vcc
	v_add_co_u32_e32 v44, vcc, s0, v78
	v_add_u32_e32 v94, 0x200, v97
	s_nop 0
	v_addc_co_u32_e32 v45, vcc, 0, v79, vcc
	v_add_co_u32_e32 v48, vcc, s39, v14
	v_add_u32_e32 v95, 0x300, v97
	s_nop 0
	v_addc_co_u32_e32 v49, vcc, 0, v15, vcc
	v_add_co_u32_e32 v56, vcc, s62, v68
	v_ashrrev_i32_e32 v108, 4, v94
	s_nop 0
	v_addc_co_u32_e32 v57, vcc, 0, v69, vcc
	v_add_co_u32_e32 v60, vcc, s62, v78
	s_mov_b32 s42, 0x5a000
	s_nop 0
	v_addc_co_u32_e32 v61, vcc, 0, v79, vcc
	v_ashrrev_i32_e32 v110, 4, v95
	v_ashrrev_i32_e32 v109, 31, v108
	v_add_co_u32_e32 v70, vcc, s42, v14
	v_ashrrev_i32_e32 v111, 31, v110
	global_load_dwordx4 v[40:43], v[12:13], off
	s_nop 0
	global_load_dwordx4 v[44:47], v[44:45], off
	v_lshl_add_u64 v[12:13], v[108:109], 0, s[4:5]
	v_addc_co_u32_e32 v71, vcc, 0, v15, vcc
	v_lshl_add_u64 v[14:15], v[110:111], 0, s[4:5]
	v_mad_u64_u32 v[50:51], s[2:3], v12, s69, v[10:11]
	v_mad_u64_u32 v[72:73], s[2:3], v14, s69, v[10:11]
	v_mad_i32_i24 v51, v13, s69, v51
	v_mad_i32_i24 v73, v15, s69, v73
	v_add_co_u32_e32 v68, vcc, s63, v68
	v_lshl_add_u64 v[50:51], v[50:51], 0, s[20:21]
	v_lshl_add_u64 v[72:73], v[72:73], 0, s[20:21]
	v_addc_co_u32_e32 v69, vcc, 0, v69, vcc
	v_lshl_add_u64 v[50:51], v[50:51], 0, v[4:5]
	v_lshl_add_u64 v[72:73], v[72:73], 0, v[4:5]
	v_add_co_u32_e32 v82, vcc, s63, v78
	v_lshl_add_u64 v[52:53], v[50:51], 0, v[8:9]
	v_lshl_add_u64 v[74:75], v[72:73], 0, v[8:9]
	v_addc_co_u32_e32 v83, vcc, 0, v79, vcc
	global_load_dwordx4 v[48:51], v[48:49], off offset:2560
	s_nop 0
	global_load_dwordx4 v[52:55], v[52:53], off offset:3072
	s_nop 0
	global_load_dwordx4 v[56:59], v[56:57], off
	s_nop 0
	global_load_dwordx4 v[60:63], v[60:61], off
	s_nop 0
	global_load_dwordx4 v[70:73], v[70:71], off offset:3072
	s_nop 0
	global_load_dwordx4 v[74:77], v[74:75], off offset:3072
	s_nop 0
	global_load_dwordx4 v[78:81], v[68:69], off
	s_nop 0
	global_load_dwordx4 v[82:85], v[82:83], off
	v_ashrrev_i32_e32 v68, 3, v97
	v_ashrrev_i32_e32 v69, 31, v68
	v_lshl_add_u64 v[112:113], v[68:69], 0, s[4:5]
	v_mad_u64_u32 v[86:87], s[2:3], v112, s69, v[10:11]
	v_mad_i32_i24 v87, v113, s69, v87
	v_lshl_add_u64 v[86:87], v[86:87], 0, s[20:21]
	v_lshl_add_u64 v[86:87], v[86:87], 0, v[8:9]
	s_movk_i32 s5, 0x1000
	v_add_co_u32_e32 v88, vcc, s5, v86
	s_mov_b32 s44, 0x3d000
	s_nop 0
	v_addc_co_u32_e32 v89, vcc, 0, v87, vcc
	v_add_co_u32_e32 v90, vcc, s44, v86
	v_mul_lo_u32 v67, v64, s36
	s_nop 0
	v_addc_co_u32_e32 v91, vcc, 0, v87, vcc
	global_load_dwordx4 v[86:89], v[88:89], off offset:512
	s_nop 0
	global_load_dwordx4 v[98:101], v[90:91], off offset:1536
	v_add3_u32 v91, s80, v104, v67
	s_waitcnt vmcnt(0) lgkmcnt(0)
	ds_write_b128 v91, v[16:19]
	ds_write_b128 v91, v[24:27] offset:17408
	ds_write_b128 v91, v[28:31] offset:34816
	s_movk_i32 s2, 0x90
	v_lshrrev_b32_e32 v116, 3, v94
	v_add_u32_e32 v96, s80, v8
	v_mul_lo_u32 v116, v116, s2
	v_ashrrev_i32_e32 v1, 3, v1
	v_add_u32_e32 v94, v96, v116
	v_lshrrev_b32_e32 v116, 3, v95
	v_mul_lo_u32 v90, v68, s2
	v_mul_lo_u32 v67, v1, s2
	v_mul_lo_u32 v116, v116, s2
	s_or_b32 s2, s4, 64
	v_add_u32_e32 v95, v96, v116
	v_add_u32_e32 v116, s24, v8
	s_ashr_i32 s3, s2, 31
	v_add_u32_e32 v92, v96, v90
	v_add_u32_e32 v93, v96, v67
	v_add_u32_e32 v96, v116, v90
	v_lshl_add_u64 v[116:117], v[64:65], 0, s[2:3]
	v_mad_u64_u32 v[118:119], s[40:41], v116, s69, v[10:11]
	v_mad_u64_u32 v[120:121], s[40:41], v116, s35, v[102:103]
	v_mad_i32_i24 v119, v117, s69, v119
	v_mad_i32_i24 v121, v117, s35, v121
	v_lshl_add_u64 v[116:117], v[118:119], 0, s[20:21]
	v_lshl_add_u64 v[64:65], v[116:117], 0, v[104:105]
	ds_write_b128 v92, v[20:23] offset:52224
	ds_write_b128 v91, v[32:35] offset:4352
	ds_write_b128 v91, v[40:43] offset:21760
	ds_write_b128 v91, v[44:47] offset:39168
	v_lshlrev_b64 v[120:121], 1, v[120:121]
	v_add_co_u32_e32 v132, vcc, s47, v64
	ds_write_b128 v93, v[36:39] offset:52224
	ds_write_b128 v91, v[48:51] offset:8704
	ds_write_b128 v91, v[56:59] offset:26112
	ds_write_b128 v91, v[60:63] offset:43520
	ds_write_b128 v94, v[52:55] offset:52224
	ds_write_b128 v91, v[70:73] offset:13056
	ds_write_b128 v91, v[78:81] offset:30464
	ds_write_b128 v91, v[82:85] offset:47872
	v_lshl_add_u64 v[224:225], s[8:9], 0, v[120:121]
	v_addc_co_u32_e32 v133, vcc, 0, v65, vcc
	v_add_co_u32_e32 v136, vcc, s0, v224
	v_lshl_add_u64 v[226:227], s[6:7], 0, v[120:121]
	s_nop 0
	v_addc_co_u32_e32 v137, vcc, 0, v225, vcc
	v_add_co_u32_e32 v140, vcc, s0, v226
	v_lshl_add_u64 v[134:135], v[106:107], 0, s[2:3]
	s_nop 0
	v_addc_co_u32_e32 v141, vcc, 0, v227, vcc
	v_add_co_u32_e32 v204, vcc, s39, v64
	v_lshl_add_u64 v[206:207], v[108:109], 0, s[2:3]
	s_nop 0
	v_addc_co_u32_e32 v205, vcc, 0, v65, vcc
	v_add_co_u32_e32 v208, vcc, s62, v224
	v_lshl_add_u64 v[220:221], v[110:111], 0, s[2:3]
	v_mad_u64_u32 v[200:201], s[40:41], v134, s69, v[10:11]
	v_mad_u64_u32 v[216:217], s[40:41], v206, s69, v[10:11]
	v_addc_co_u32_e32 v209, vcc, 0, v225, vcc
	v_mad_u64_u32 v[222:223], s[40:41], v220, s69, v[10:11]
	ds_write_b128 v95, v[74:77] offset:52224
	ds_write_b128 v96, v[86:89]
	ds_write_b128 v96, v[98:101] offset:4608
	v_lshl_add_u64 v[116:117], v[116:117], 0, v[4:5]
	v_mad_i32_i24 v201, v135, s69, v201
	v_mad_i32_i24 v217, v207, s69, v217
	v_add_co_u32_e32 v212, vcc, s62, v226
	v_mad_i32_i24 v223, v221, s69, v223
	v_lshl_add_u64 v[128:129], v[116:117], 0, v[8:9]
	v_lshl_add_u64 v[134:135], v[200:201], 0, s[20:21]
	v_lshl_add_u64 v[206:207], v[216:217], 0, s[20:21]
	v_addc_co_u32_e32 v213, vcc, 0, v227, vcc
	v_lshl_add_u64 v[220:221], v[222:223], 0, s[20:21]
	global_load_dwordx4 v[116:119], v[64:65], off offset:1536
	s_nop 0
	global_load_dwordx4 v[128:131], v[128:129], off offset:3072
	v_lshl_add_u64 v[134:135], v[134:135], 0, v[4:5]
	v_lshl_add_u64 v[206:207], v[206:207], 0, v[4:5]
	v_add_co_u32_e32 v64, vcc, s42, v64
	v_lshl_add_u64 v[220:221], v[220:221], 0, v[4:5]
	v_lshl_add_u64 v[200:201], v[134:135], 0, v[8:9]
	v_lshl_add_u64 v[216:217], v[206:207], 0, v[8:9]
	v_addc_co_u32_e32 v65, vcc, 0, v65, vcc
	v_lshl_add_u64 v[232:233], v[220:221], 0, v[8:9]
	global_load_dwordx4 v[120:123], v[224:225], off
	global_load_dwordx4 v[124:127], v[226:227], off
	s_nop 0
	global_load_dwordx4 v[132:135], v[132:133], off offset:2048
	s_nop 0
	global_load_dwordx4 v[200:203], v[200:201], off offset:3072
	s_nop 0
	global_load_dwordx4 v[136:139], v[136:137], off
	s_nop 0
	global_load_dwordx4 v[140:143], v[140:141], off
	s_nop 0
	global_load_dwordx4 v[204:207], v[204:205], off offset:2560
	s_nop 0
	global_load_dwordx4 v[216:219], v[216:217], off offset:3072
	s_nop 0
	global_load_dwordx4 v[208:211], v[208:209], off
	s_nop 0
	global_load_dwordx4 v[212:215], v[212:213], off
	s_nop 0
	global_load_dwordx4 v[220:223], v[64:65], off offset:3072
	s_nop 0
	global_load_dwordx4 v[232:235], v[232:233], off offset:3072
	v_add_co_u32_e32 v64, vcc, s63, v224
	s_nop 1
	v_addc_co_u32_e32 v65, vcc, 0, v225, vcc
	v_add_co_u32_e32 v228, vcc, s63, v226
	s_nop 1
	v_addc_co_u32_e32 v229, vcc, 0, v227, vcc
	global_load_dwordx4 v[224:227], v[64:65], off
	s_nop 0
	global_load_dwordx4 v[228:231], v[228:229], off
	v_lshl_add_u64 v[64:65], v[68:69], 0, s[2:3]
	v_mad_u64_u32 v[10:11], s[2:3], v64, s69, v[10:11]
	v_mad_i32_i24 v11, v65, s69, v11
	v_lshl_add_u64 v[10:11], v[10:11], 0, s[20:21]
	v_lshl_add_u64 v[10:11], v[10:11], 0, v[8:9]
	v_add_co_u32_e32 v64, vcc, s5, v10
	s_add_u32 s3, s74, s20
	s_nop 0
	v_addc_co_u32_e32 v65, vcc, 0, v11, vcc
	v_add_co_u32_e32 v10, vcc, s44, v10
	s_addc_u32 s5, s75, s21
	s_nop 0
	v_addc_co_u32_e32 v11, vcc, 0, v11, vcc
	global_load_dwordx4 v[236:239], v[64:65], off offset:512
	global_load_dwordx4 v[240:243], v[10:11], off offset:1536
	s_lshl_b32 s35, s34, 1
	s_add_u32 s40, s3, s35
	s_addc_u32 s41, s5, 0
	v_add_u32_e32 v69, s25, v8
	v_lshl_add_u64 v[70:71], s[40:41], 0, v[8:9]
	v_and_b32_e32 v8, 7, v97
	v_lshlrev_b32_e32 v8, 4, v8
	v_mad_u64_u32 v[10:11], s[40:41], v112, s69, v[8:9]
	v_mad_i32_i24 v11, v113, s69, v11
	v_lshl_add_u64 v[76:77], s[22:23], 0, v[10:11]
	v_mad_u64_u32 v[10:11], s[40:41], v14, s69, v[4:5]
	v_mad_i32_i24 v11, v15, s69, v11
	v_lshl_add_u64 v[10:11], v[10:11], 0, v[8:9]
	v_lshl_add_u64 v[78:79], s[18:19], 0, v[10:11]
	v_mad_u64_u32 v[10:11], s[40:41], v12, s69, v[4:5]
	v_mad_i32_i24 v11, v13, s69, v11
	v_lshl_add_u64 v[10:11], v[10:11], 0, v[8:9]
	v_lshl_add_u64 v[80:81], s[18:19], 0, v[10:11]
	v_mad_u64_u32 v[10:11], s[40:41], v6, s69, v[4:5]
	v_mad_i32_i24 v11, v7, s69, v11
	v_mad_u64_u32 v[4:5], s[40:41], v2, s69, v[4:5]
	v_lshl_add_u64 v[6:7], v[10:11], 0, v[8:9]
	v_mad_i32_i24 v5, v3, s69, v5
	v_lshl_add_u64 v[82:83], s[18:19], 0, v[6:7]
	v_and_b32_e32 v6, 0xf0, v114
	v_mov_b32_e32 v7, v0
	v_lshl_add_u64 v[4:5], v[4:5], 0, v[8:9]
	v_mad_u64_u32 v[10:11], s[40:41], v2, s69, v[6:7]
	v_lshl_add_u64 v[86:87], s[18:19], 0, v[4:5]
	v_mad_u64_u32 v[4:5], s[40:41], v2, s50, 0
	v_mad_i32_i24 v11, v3, s69, v11
	v_mad_i32_i24 v3, v3, s50, v5
	v_or_b32_e32 v2, v4, v6
	s_mov_b32 s2, 0
	v_add_u32_e32 v72, s4, v1
	v_add_u32_e32 v74, s4, v68
	v_lshl_add_u64 v[84:85], s[22:23], 0, v[10:11]
	v_lshl_add_u64 v[88:89], s[22:23], 0, v[2:3]
	s_mov_b32 s2, -1
	v_subrev_u32_e32 v72, 64, v72
	v_subrev_u32_e32 v74, 64, v74
	s_mov_b32 s98, 0xff00ff
	s_mov_b32 s99, 0xff00ff00
	s_cmp_eq_u32 s34, 0
	s_cselect_b32 s98, s98, s99
	s_mov_b32 s99, s98
	v_lshl_add_u64 v[50:51], v[84:85], 0, s[20:21]
	v_add_co_u32_e32 v2, vcc, 0x81f1000, v50
	v_lshl_add_u64 v[62:63], v[88:89], 0, s[20:21]
	s_nop 0
	v_addc_co_u32_e32 v3, vcc, 0, v51, vcc
	v_add_co_u32_e32 v10, vcc, 0x1a230000, v62
	s_nop 0
	v_addc_co_u32_e32 v11, vcc, 0, v63, vcc
	v_add_co_u32_e32 v14, vcc, 0x17230000, v62
	v_subrev_u32_e32 v244, s22, v2
	s_nop 0
	v_addc_co_u32_e32 v15, vcc, 0, v63, vcc
	v_add_co_u32_e32 v18, vcc, 0x820f000, v50
	v_subrev_u32_e32 v245, s22, v10
	s_nop 0
	v_addc_co_u32_e32 v19, vcc, 0, v51, vcc
	v_add_co_u32_e32 v26, vcc, 0x1a236000, v62
	v_lshl_add_u64 v[6:7], v[86:87], 0, s[20:21]
	s_nop 0
	v_addc_co_u32_e32 v27, vcc, 0, v63, vcc
	v_add_co_u32_e32 v30, vcc, 0x17236000, v62
	v_subrev_u32_e32 v246, s22, v14
	s_nop 0
	v_addc_co_u32_e32 v31, vcc, 0, v63, vcc
	v_add_co_u32_e32 v34, vcc, 0x822d000, v50
	v_subrev_u32_e32 v247, s22, v6
	s_nop 0
	v_addc_co_u32_e32 v35, vcc, 0, v51, vcc
	v_add_co_u32_e32 v42, vcc, 0x1a23c000, v62
	v_subrev_u32_e32 v248, s22, v18
	s_nop 0
	v_addc_co_u32_e32 v43, vcc, 0, v63, vcc
	v_subrev_u32_e32 v249, s22, v26
	v_add_co_u32_e32 v46, vcc, 0x1723c000, v62
	v_lshl_add_u64 v[22:23], v[82:83], 0, s[20:21]
	v_subrev_u32_e32 v250, s22, v30
	v_addc_co_u32_e32 v47, vcc, 0, v63, vcc
	v_subrev_u32_e32 v251, s22, v22
	v_add_co_u32_e32 v50, vcc, 0x824b000, v50
	v_subrev_u32_e32 v252, s22, v34
	s_nop 0
	v_addc_co_u32_e32 v51, vcc, 0, v51, vcc
	v_subrev_u32_e32 v253, s22, v42
	v_add_co_u32_e32 v58, vcc, 0x1a242000, v62
	v_lshl_add_u64 v[38:39], v[80:81], 0, s[20:21]
	v_subrev_u32_e32 v112, s22, v46
	v_addc_co_u32_e32 v59, vcc, 0, v63, vcc
	v_subrev_u32_e32 v113, s22, v38
	v_add_co_u32_e32 v62, vcc, 0x17242000, v62
	v_subrev_u32_e32 v114, s22, v50
	s_nop 0
	v_addc_co_u32_e32 v63, vcc, 0, v63, vcc
	v_lshl_add_u64 v[102:103], v[76:77], 0, s[20:21]
	v_subrev_u32_e32 v115, s22, v58
	v_add_co_u32_e32 v98, vcc, 0x81f2000, v102
	v_lshl_add_u64 v[54:55], v[78:79], 0, s[20:21]
	v_subrev_u32_e32 v106, s22, v62
	v_addc_co_u32_e32 v99, vcc, 0, v103, vcc
	v_subrev_u32_e32 v107, s22, v54
	v_add_co_u32_e32 v102, vcc, 0x822e000, v102
	v_subrev_u32_e32 v108, s22, v98
	s_nop 0
	v_addc_co_u32_e32 v103, vcc, 0, v103, vcc
	v_subrev_u32_e32 v109, s22, v102
	v_mov_b32_e32 v76, v106
	v_mov_b32_e32 v77, v107
	v_mov_b32_e32 v78, v108
	v_mov_b32_e32 v79, v109
	v_writelane_b32 v150, s20, 0
	v_writelane_b32 v150, s21, 1
	s_mov_b64 s[20:21], s[22:23]
	s_mov_b64 s[40:41], s[22:23]
	v_lshlrev_b32_e32 v84, 11, v74
	v_lshlrev_b32_e32 v85, 11, v72
	v_add_u32_e32 v84, v84, v70
	v_add_u32_e32 v85, v85, v70
	v_subrev_u32_e32 v84, s22, v84
	v_subrev_u32_e32 v85, s22, v85
.Lgp_even:
	s_waitcnt lgkmcnt(0)
	s_barrier
	s_cmp_lt_i32 s2, 0
	s_cbranch_scc1 .Lgp_e_nost
	s_bitcmp1_b32 s2, 0
	s_cselect_b32 s3, 0x2400, 0
	v_add_u32_e32 v73, s3, v69
	v_add_u32_e32 v75, v73, v90
	ds_read_b128 v[106:109], v75
	v_add_u32_e32 v73, v73, v67
	ds_read_b128 v[80:83], v73
	s_waitcnt lgkmcnt(1)
	global_store_dwordx4 v84, v[106:109], s[22:23] offset:512
	s_waitcnt lgkmcnt(0)
	global_store_dwordx4 v85, v[80:83], s[22:23] offset:512

; #define LDS_BARRIER() do { asm volatile("s_waitcnt lgkmcnt(0)" ::: "memory"); __builtin_amdgcn_s_barrier(); asm volatile("" ::: "memory"); } while (0)
; #define GDN_STORE_O(nn) do { const LAS bf16_t* ob_ = OTb + ((nn) & 1) * 4608; _Pragma("unroll") for (int k_ = 0; k_ < 2; ++k_) { const int vi_ = pt_ + 256 * k_, row_ = vi_ >> 3, c8_ = (vi_ & 7) * 8; \
;             *(u32x4*)(Y + (size_t)(b * T_ + 64 * (nn) + row_) * D_ + 256 + h * 128 + 64 * dvh + c8_) = *(const LAS u32x4*)(ob_ + row_ * 72 + c8_); } } while (0)
; __device__ __forceinline__ void gdn_scan(const Ctx& c, const Params& p, int e) {
;     ...
;             for (int n = 0; n < 128; ++n) {
;                 LDS_BARRIER();
;                 if (n + 1 < 128) GDN_LOAD_TILES(n + 1);
;                 if (n >= 1) GDN_STORE_O(n - 1);
;                 LDS_BARRIER();
;                 if (n + 1 < 128) GDN_STORE_TILES();
.Lgp_e_nold:
	s_add_i32 s2, s2, 1
	s_waitcnt lgkmcnt(0)
	s_barrier
	v_add_u32_e32 v72, 64, v72
	v_add_u32_e32 v74, 64, v74
	v_add_u32_e32 v84, 0x20000, v84
	v_add_u32_e32 v85, 0x20000, v85
	s_cmpk_eq_i32 s2, 0x7e
	s_cbranch_scc1 .Lgp_e_w0
	s_waitcnt vmcnt(18)
	s_branch .Lgp_e_wr

; #define LDS_BARRIER() do { asm volatile("s_waitcnt lgkmcnt(0)" ::: "memory"); __builtin_amdgcn_s_barrier(); asm volatile("" ::: "memory"); } while (0)
; #define GDN_STORE_O(nn) do { const LAS bf16_t* ob_ = OTb + ((nn) & 1) * 4608; _Pragma("unroll") for (int k_ = 0; k_ < 2; ++k_) { const int vi_ = pt_ + 256 * k_, row_ = vi_ >> 3, c8_ = (vi_ & 7) * 8; \
;             *(u32x4*)(Y + (size_t)(b * T_ + 64 * (nn) + row_) * D_ + 256 + h * 128 + 64 * dvh + c8_) = *(const LAS u32x4*)(ob_ + row_ * 72 + c8_); } } while (0)
; __device__ __forceinline__ void gdn_scan(const Ctx& c, const Params& p, int e) {
;     ...
;             for (int n = 0; n < 128; ++n) {
;                 LDS_BARRIER();
;                 if (n + 1 < 128) GDN_LOAD_TILES(n + 1);
;                 if (n >= 1) GDN_STORE_O(n - 1);
;                 LDS_BARRIER();
;                 if (n + 1 < 128) GDN_STORE_TILES();
.Lgp_e_wr:
	ds_write_b128 v91, v[116:119]
	ds_write_b128 v91, v[120:123] offset:17408
	ds_write_b128 v91, v[124:127] offset:34816
	ds_write_b128 v92, v[128:131] offset:52224
	ds_write_b128 v91, v[132:135] offset:4352
	ds_write_b128 v91, v[136:139] offset:21760
	ds_write_b128 v91, v[140:143] offset:39168
	ds_write_b128 v93, v[200:203] offset:52224
	ds_write_b128 v91, v[204:207] offset:8704
	ds_write_b128 v91, v[208:211] offset:26112
	ds_write_b128 v91, v[212:215] offset:43520
	ds_write_b128 v94, v[216:219] offset:52224
	ds_write_b128 v91, v[220:223] offset:13056
	ds_write_b128 v91, v[224:227] offset:30464
	ds_write_b128 v91, v[228:231] offset:47872
	ds_write_b128 v95, v[232:235] offset:52224
	ds_write_b128 v96, v[236:239]
	ds_write_b128 v96, v[240:243] offset:4608
	s_cmpk_eq_i32 s2, 0x7e
	s_cbranch_scc1 .Lgp_done
	s_waitcnt lgkmcnt(0)
	s_barrier
	s_bitcmp1_b32 s2, 0
	s_cselect_b32 s3, 0x2400, 0
	v_add_u32_e32 v73, s3, v69
	v_add_u32_e32 v75, v73, v90
	ds_read_b128 v[106:109], v75
	v_add_u32_e32 v73, v73, v67
	ds_read_b128 v[80:83], v73
	s_waitcnt lgkmcnt(1)
	global_store_dwordx4 v84, v[106:109], s[22:23] offset:512
	s_waitcnt lgkmcnt(0)
	global_store_dwordx4 v85, v[80:83], s[22:23] offset:512
	global_load_dwordx4 v[116:119], v244, s[20:21] offset:1536
	global_load_dwordx4 v[120:123], v245, s[40:41]
	s_mov_b64 exec, s[98:99]
	global_load_dwordx4 v[124:127], v246, s[40:41]
	s_mov_b64 exec, -1
	global_load_dwordx4 v[128:131], v247, s[20:21]
	global_load_dwordx4 v[132:135], v248, s[20:21] offset:2048
	global_load_dwordx4 v[136:139], v249, s[40:41]
	s_mov_b64 exec, s[98:99]
	global_load_dwordx4 v[140:143], v250, s[40:41]
	s_mov_b64 exec, -1
	global_load_dwordx4 v[200:203], v251, s[20:21]
	global_load_dwordx4 v[204:207], v252, s[20:21] offset:2560
	global_load_dwordx4 v[208:211], v253, s[40:41]
	s_mov_b64 exec, s[98:99]
	global_load_dwordx4 v[212:215], v112, s[40:41]
	s_mov_b64 exec, -1
	global_load_dwordx4 v[216:219], v113, s[20:21]
	global_load_dwordx4 v[220:223], v114, s[20:21] offset:3072
	global_load_dwordx4 v[224:227], v115, s[40:41]
	s_mov_b64 exec, s[98:99]
	global_load_dwordx4 v[228:231], v76, s[40:41]
	s_mov_b64 exec, -1
	global_load_dwordx4 v[232:235], v77, s[20:21]
	global_load_dwordx4 v[236:239], v78, s[20:21] offset:512
	global_load_dwordx4 v[240:243], v79, s[20:21] offset:1536
	s_add_u32 s20, s20, 0x78800
	s_addc_u32 s21, s21, 0
	s_add_u32 s40, s40, 0x18000
	s_addc_u32 s41, s41, 0
	s_add_i32 s2, s2, 1
	s_waitcnt lgkmcnt(0)
	s_barrier
	v_add_u32_e32 v72, 64, v72
	v_add_u32_e32 v74, 64, v74
	v_add_u32_e32 v84, 0x20000, v84
	v_add_u32_e32 v85, 0x20000, v85
	s_waitcnt vmcnt(18)
	ds_write_b128 v91, v[2:5]
	ds_write_b128 v91, v[10:13] offset:17408
	ds_write_b128 v91, v[14:17] offset:34816
	ds_write_b128 v92, v[6:9] offset:52224
	ds_write_b128 v91, v[18:21] offset:4352
	ds_write_b128 v91, v[26:29] offset:21760
	ds_write_b128 v91, v[30:33] offset:39168
	ds_write_b128 v93, v[22:25] offset:52224
	ds_write_b128 v91, v[34:37] offset:8704
	ds_write_b128 v91, v[42:45] offset:26112
	ds_write_b128 v91, v[46:49] offset:43520
	ds_write_b128 v94, v[38:41] offset:52224
	ds_write_b128 v91, v[50:53] offset:13056
	ds_write_b128 v91, v[58:61] offset:30464
	ds_write_b128 v91, v[62:65] offset:47872
	ds_write_b128 v95, v[54:57] offset:52224
	ds_write_b128 v96, v[98:101]
	ds_write_b128 v96, v[102:105] offset:4608
	s_branch .Lgp_even
